# attention items permuted so each workgroup handles query tiles resident on its own XCD (QB reads and MIXIN writes stay XCD-local)
# baseline (speedup 1.0000x reference)
.LBB0_171:
	s_mov_b64 s[6:7], 0
	s_mov_b64 s[4:5], -1
	s_cmp_lt_i32 s13, 32
	s_mov_b64 s[0:1], -1
	s_mov_b32 s42, s13
	s_mov_b64 s[10:11], -1
	s_cbranch_scc1 .LBB0_185
	s_cmp_gt_u32 s13, 63
	s_mov_b64 s[36:37], -1
	s_cbranch_scc0 .LBB0_183
	s_cmpk_gt_u32 s13, 0x13f
	s_mov_b64 s[0:1], -1
	s_cbranch_scc0 .LBB0_181
	s_cmpk_gt_u32 s13, 0x1bf
	s_mov_b64 s[10:11], -1
	s_cbranch_scc0 .LBB0_179
	s_cmpk_gt_u32 s13, 0x23f
	s_cbranch_scc0 .LBB0_177
	s_add_i32 s42, s13, 0xfffffdc0
	s_bfe_u32 s22, s42, 0x20006
	s_lshl_b32 s22, s22, 6
	s_bfe_u32 s25, s42, 0x20001
	s_lshl_b32 s25, s25, 4
	s_or_b32 s22, s22, s25
	s_bfe_u32 s25, s42, 0x10005
	s_lshl_b32 s25, s25, 3
	s_or_b32 s22, s22, s25
	s_and_b32 s25, s42, 1
	s_lshl_b32 s25, s25, 2
	s_or_b32 s22, s22, s25
	s_bfe_u32 s25, s42, 0x20003
	s_or_b32 s42, s22, s25
	s_mov_b64 s[0:1], 0

.LBB0_181:
	s_mov_b64 s[36:37], 0
	s_andn2_b64 vcc, exec, s[0:1]
	s_mov_b64 s[0:1], 0
	s_cbranch_vccnz .LBB0_183
	s_sub_i32 s42, s13, 64
	s_and_b32 s22, s42, 7
	s_lshl_b32 s22, s22, 2
	s_bfe_u32 s25, s42, 0x20003
	s_or_b32 s22, s22, s25
	s_and_b32 s42, s42, 0xe0
	s_or_b32 s42, s42, s22
	s_mov_b64 s[0:1], -1
	s_mov_b64 s[6:7], 0
	s_mov_b64 s[10:11], 0
